# gdn scan producer: the four half-masked U loads issued together under one EXEC toggle pair
# speedup vs baseline: 1.0013x; 1.0013x over previous
; __device__ __forceinline__ void gdn_scan(const Ctx& c, const Params& p, int e) {
;     ...
;                 if (n + 1 < 128) GDN_LOAD_TILES(n + 1);
.Lgp_e_nost:
	s_cmpk_eq_i32 s2, 0x7d
	s_cbranch_scc1 .Lgp_e_nold
	global_load_dwordx4 v[2:5], v244, s[20:21] offset:1536
	global_load_dwordx4 v[10:13], v245, s[40:41]
	global_load_dwordx4 v[6:9], v247, s[20:21]
	global_load_dwordx4 v[18:21], v248, s[20:21] offset:2048
	global_load_dwordx4 v[26:29], v249, s[40:41]
	global_load_dwordx4 v[22:25], v251, s[20:21]
	global_load_dwordx4 v[34:37], v252, s[20:21] offset:2560
	global_load_dwordx4 v[42:45], v253, s[40:41]
	global_load_dwordx4 v[38:41], v113, s[20:21]
	global_load_dwordx4 v[50:53], v114, s[20:21] offset:3072
	global_load_dwordx4 v[58:61], v115, s[40:41]
	global_load_dwordx4 v[54:57], v77, s[20:21]
	global_load_dwordx4 v[98:101], v78, s[20:21] offset:512
	global_load_dwordx4 v[102:105], v79, s[20:21] offset:1536
	s_mov_b64 exec, s[98:99]
	global_load_dwordx4 v[14:17], v246, s[40:41]
	global_load_dwordx4 v[30:33], v250, s[40:41]
	global_load_dwordx4 v[46:49], v112, s[40:41]
	global_load_dwordx4 v[62:65], v76, s[40:41]
	s_mov_b64 exec, -1
	s_add_u32 s20, s20, 0x78800
	s_addc_u32 s21, s21, 0
	s_add_u32 s40, s40, 0x18000
	s_addc_u32 s41, s41, 0

; #define LDS_BARRIER() do { asm volatile("s_waitcnt lgkmcnt(0)" ::: "memory"); __builtin_amdgcn_s_barrier(); asm volatile("" ::: "memory"); } while (0)
; #define GDN_STORE_O(nn) do { const LAS bf16_t* ob_ = OTb + ((nn) & 1) * 4608; _Pragma("unroll") for (int k_ = 0; k_ < 2; ++k_) { const int vi_ = pt_ + 256 * k_, row_ = vi_ >> 3, c8_ = (vi_ & 7) * 8; \
;             *(u32x4*)(Y + (size_t)(b * T_ + 64 * (nn) + row_) * D_ + 256 + h * 128 + 64 * dvh + c8_) = *(const LAS u32x4*)(ob_ + row_ * 72 + c8_); } } while (0)
; __device__ __forceinline__ void gdn_scan(const Ctx& c, const Params& p, int e) {
;     ...
;         if (producer) {
;             int pt_ = ptid; asm volatile("" : "+v"(pt_));
;             u32x4 tq[4], tk[4], tw[4], tu[4], tqk[2];
;             const int prow = pt_ >> 4, pc8 = (pt_ & 15) * 8;
;             const int qrow = pt_ >> 3, qc8 = (pt_ & 7) * 8;
;             GDN_LOAD_TILES(0); GDN_STORE_TILES();
;             for (int n = 0; n < 128; ++n) {
;                 LDS_BARRIER();
;                 if (n + 1 < 128) GDN_LOAD_TILES(n + 1);
;                 if (n >= 1) GDN_STORE_O(n - 1);
;                 LDS_BARRIER();
;                 if (n + 1 < 128) GDN_STORE_TILES();
;             }
.Lgp_e_wr:
	ds_write_b128 v91, v[116:119]
	ds_write_b128 v91, v[120:123] offset:17408
	ds_write_b128 v91, v[124:127] offset:34816
	ds_write_b128 v92, v[128:131] offset:52224
	ds_write_b128 v91, v[132:135] offset:4352
	ds_write_b128 v91, v[136:139] offset:21760
	ds_write_b128 v91, v[140:143] offset:39168
	ds_write_b128 v93, v[200:203] offset:52224
	ds_write_b128 v91, v[204:207] offset:8704
	ds_write_b128 v91, v[208:211] offset:26112
	ds_write_b128 v91, v[212:215] offset:43520
	ds_write_b128 v94, v[216:219] offset:52224
	ds_write_b128 v91, v[220:223] offset:13056
	ds_write_b128 v91, v[224:227] offset:30464
	ds_write_b128 v91, v[228:231] offset:47872
	ds_write_b128 v95, v[232:235] offset:52224
	ds_write_b128 v96, v[236:239]
	ds_write_b128 v96, v[240:243] offset:4608
	s_cmpk_eq_i32 s2, 0x7e
	s_cbranch_scc1 .Lgp_done
	s_waitcnt lgkmcnt(0)
	s_barrier
	s_bitcmp1_b32 s2, 0
	s_cselect_b32 s3, 0x2400, 0
	v_add_u32_e32 v73, s3, v69
	v_add_u32_e32 v75, v73, v90
	ds_read_b128 v[106:109], v75
	v_ashrrev_i32_e32 v75, 31, v74
	v_lshlrev_b64 v[110:111], 11, v[74:75]
	v_lshl_add_u64 v[110:111], v[70:71], 0, v[110:111]
	v_add_u32_e32 v73, v73, v67
	s_waitcnt lgkmcnt(0)
	global_store_dwordx4 v[110:111], v[106:109], off offset:512
	ds_read_b128 v[106:109], v73
	v_ashrrev_i32_e32 v73, 31, v72
	v_lshlrev_b64 v[110:111], 11, v[72:73]
	v_lshl_add_u64 v[110:111], v[70:71], 0, v[110:111]
	s_waitcnt lgkmcnt(0)
	global_store_dwordx4 v[110:111], v[106:109], off offset:512
	global_load_dwordx4 v[116:119], v244, s[20:21] offset:1536
	global_load_dwordx4 v[120:123], v245, s[40:41]
	global_load_dwordx4 v[128:131], v247, s[20:21]
	global_load_dwordx4 v[132:135], v248, s[20:21] offset:2048
	global_load_dwordx4 v[136:139], v249, s[40:41]
	global_load_dwordx4 v[200:203], v251, s[20:21]
	global_load_dwordx4 v[204:207], v252, s[20:21] offset:2560
	global_load_dwordx4 v[208:211], v253, s[40:41]
	global_load_dwordx4 v[216:219], v113, s[20:21]
	global_load_dwordx4 v[220:223], v114, s[20:21] offset:3072
	global_load_dwordx4 v[224:227], v115, s[40:41]
	global_load_dwordx4 v[232:235], v77, s[20:21]
	global_load_dwordx4 v[236:239], v78, s[20:21] offset:512
	global_load_dwordx4 v[240:243], v79, s[20:21] offset:1536
	s_mov_b64 exec, s[98:99]
	global_load_dwordx4 v[124:127], v246, s[40:41]
	global_load_dwordx4 v[140:143], v250, s[40:41]
	global_load_dwordx4 v[212:215], v112, s[40:41]
	global_load_dwordx4 v[228:231], v76, s[40:41]
	s_mov_b64 exec, -1
	s_add_u32 s20, s20, 0x78800
	s_addc_u32 s21, s21, 0
	s_add_u32 s40, s40, 0x18000
	s_addc_u32 s41, s41, 0
	s_add_i32 s2, s2, 1
	s_waitcnt lgkmcnt(0)
	s_barrier
	v_add_u32_e32 v72, 64, v72
	v_add_u32_e32 v74, 64, v74
	s_waitcnt vmcnt(18)
	ds_write_b128 v91, v[2:5]
	ds_write_b128 v91, v[10:13] offset:17408
	ds_write_b128 v91, v[14:17] offset:34816
	ds_write_b128 v92, v[6:9] offset:52224
	ds_write_b128 v91, v[18:21] offset:4352
	ds_write_b128 v91, v[26:29] offset:21760
	ds_write_b128 v91, v[30:33] offset:39168
	ds_write_b128 v93, v[22:25] offset:52224
	ds_write_b128 v91, v[34:37] offset:8704
	ds_write_b128 v91, v[42:45] offset:26112
	ds_write_b128 v91, v[46:49] offset:43520
	ds_write_b128 v94, v[38:41] offset:52224
	ds_write_b128 v91, v[50:53] offset:13056
	ds_write_b128 v91, v[58:61] offset:30464
	ds_write_b128 v91, v[62:65] offset:47872
	ds_write_b128 v95, v[54:57] offset:52224
	ds_write_b128 v96, v[98:101]
	ds_write_b128 v96, v[102:105] offset:4608
	s_branch .Lgp_even
